# A2: near-diagonal bias+mask tile rewritten: one base address, immediate-offset ds_read_b32 window, cmp/add/cndmask (no exec branches)
# speedup vs baseline: 1.0106x; 1.0106x over previous
; #define SBAR() __builtin_amdgcn_sched_barrier(0)
; #define A2_LOADT(t) do { const size_t ro_ = (size_t)((t) * 64 + sr) * D + sc; \
;         sk0 = att::load8(c.K + ro_); sk1 = att::load8(c.K + ro_ + 32 * D); sv00 = att::load8(c.V0 + ro_); sv01 = att::load8(c.V0 + ro_ + 32 * D); sv10 = att::load8(c.V1 + ro_); sv11 = att::load8(c.V1 + ro_ + 32 * D); } while (0)
; __device__ __forceinline__ void qkt_rt(f32x16& p0, f32x16& p1, const char* Kb, int r32, int hi, const bf16x8* qr) {
;     p0 = f32x16{}; p1 = f32x16{};
;     const char* kb[4];
; #pragma unroll
;     for (int dd = 0; dd < 4; ++dd) kb[dd] = Kb + KSWZ(r32, (dd * 16 + hi * 8) * 2);
; #pragma unroll
;     for (int d0 = 0; d0 < 8; ++d0) { const char* a = kb[d0 & 3] + (d0 >> 2) * 128;
;         bf16x8 b0 = *reinterpret_cast<const bf16x8*>(a);
;         bf16x8 b1 = *reinterpret_cast<const bf16x8*>(a + 32 * 256);
;         p0 = __builtin_amdgcn_mfma_f32_32x32x16_bf16(b0, qr[d0], p0, 0, 0, 0);
;         p1 = __builtin_amdgcn_mfma_f32_32x32x16_bf16(b1, qr[d0], p1, 0, 0, 0); }
; }
; __device__ __forceinline__ void attn2_block(const Blk& c, char* lds) {
;     ...
;         for (int s = 0; s <= NT; ++s) {
;             const int par = s & 1;
;             if (s + 1 < NT) A2_LOADT(s + 1);
;             SBAR();
;             if (s < NT) {
;                 f32x16 p0, p1; float mn, al; bf16x8 pa0, pa1, pa2, pa3;
;                 qkt_rt(p0, p1, lds + L_K + par * SHM_K, r32, hi, qr);
;                 const int kb_ = s * 64;
.LBB0_552:
	v_lshl_add_u64 v[4:5], v[108:109], 0, s[82:83]
	v_add_co_u32_e32 v6, vcc, 0x1c004000, v4
	s_and_b32 s88, s30, 1
	s_nop 0
	v_addc_co_u32_e32 v7, vcc, 0, v5, vcc
	v_add_co_u32_e32 v4, vcc, 0x1c006000, v4
	s_nop 1
	v_addc_co_u32_e32 v5, vcc, 0, v5, vcc
	global_load_dwordx4 v[52:55], v[6:7], off
	global_load_dwordx4 v[56:59], v[4:5], off
	v_lshl_add_u64 v[4:5], v[110:111], 0, s[82:83]
	v_add_co_u32_e32 v6, vcc, 0x1e004000, v4
	s_nop 1
	v_addc_co_u32_e32 v7, vcc, 0, v5, vcc
	v_add_co_u32_e32 v8, vcc, 0x1e006000, v4
	s_nop 1
	v_addc_co_u32_e32 v9, vcc, 0, v5, vcc
	global_load_dwordx4 v[60:63], v[6:7], off
	global_load_dwordx4 v[64:67], v[8:9], off
	v_add_co_u32_e32 v6, vcc, 0x1e404000, v4
	s_nop 1
	v_addc_co_u32_e32 v7, vcc, 0, v5, vcc
	v_add_co_u32_e32 v4, vcc, 0x1e406000, v4
	s_nop 1
	v_addc_co_u32_e32 v5, vcc, 0, v5, vcc
	global_load_dwordx4 v[68:71], v[6:7], off
	global_load_dwordx4 v[72:75], v[4:5], off
	s_lshl_b32 s10, s88, 14
	s_add_i32 s10, s10, 0
	s_add_i32 s10, s10, 0x10000
	v_add3_u32 v40, s10, v121, v119
	ds_read_b128 v[4:7], v40
	v_add3_u32 v41, s10, v122, v119
	ds_read_b128 v[36:39], v41
	v_add3_u32 v42, s10, v123, v119
	v_add3_u32 v43, s10, v124, v119
	s_add_i32 s10, s84, 63
	s_cmp_le_i32 s10, s86
	s_waitcnt vmcnt(13) lgkmcnt(1)
	v_mfma_f32_32x32x16_bf16 v[20:35], v[4:7], v[104:107], 0
	ds_read_b128 v[4:7], v40 offset:8192
	s_waitcnt vmcnt(12) lgkmcnt(1)
	v_mfma_f32_32x32x16_bf16 v[20:35], v[36:39], v[100:103], v[20:35]
	ds_read_b128 v[36:39], v41 offset:8192
	s_waitcnt lgkmcnt(1)
	v_mfma_f32_32x32x16_bf16 v[4:19], v[4:7], v[104:107], 0
	s_waitcnt lgkmcnt(0)
	v_mfma_f32_32x32x16_bf16 v[4:19], v[36:39], v[100:103], v[4:19]
	ds_read_b128 v[36:39], v42
	s_waitcnt vmcnt(11) lgkmcnt(0)
	v_mfma_f32_32x32x16_bf16 v[20:35], v[36:39], v[96:99], v[20:35]
	ds_read_b128 v[36:39], v42 offset:8192
	s_waitcnt lgkmcnt(0)
	v_mfma_f32_32x32x16_bf16 v[4:19], v[36:39], v[96:99], v[4:19]
	ds_read_b128 v[36:39], v43
	s_waitcnt vmcnt(10) lgkmcnt(0)
	v_mfma_f32_32x32x16_bf16 v[20:35], v[36:39], v[92:95], v[20:35]
	ds_read_b128 v[36:39], v43 offset:8192
	s_waitcnt lgkmcnt(0)
	v_mfma_f32_32x32x16_bf16 v[4:19], v[36:39], v[92:95], v[4:19]
	ds_read_b128 v[36:39], v40 offset:128
	s_waitcnt vmcnt(9) lgkmcnt(0)
	v_mfma_f32_32x32x16_bf16 v[20:35], v[36:39], v[88:91], v[20:35]
	ds_read_b128 v[36:39], v40 offset:8320
	s_waitcnt lgkmcnt(0)
	v_mfma_f32_32x32x16_bf16 v[4:19], v[36:39], v[88:91], v[4:19]
	ds_read_b128 v[36:39], v41 offset:128
	s_waitcnt vmcnt(8) lgkmcnt(0)
	v_mfma_f32_32x32x16_bf16 v[20:35], v[36:39], v[84:87], v[20:35]
	ds_read_b128 v[36:39], v41 offset:8320
	s_waitcnt lgkmcnt(0)
	v_mfma_f32_32x32x16_bf16 v[4:19], v[36:39], v[84:87], v[4:19]
	ds_read_b128 v[36:39], v42 offset:128
	s_waitcnt vmcnt(7) lgkmcnt(0)
	v_mfma_f32_32x32x16_bf16 v[20:35], v[36:39], v[80:83], v[20:35]
	ds_read_b128 v[36:39], v42 offset:8320
	s_waitcnt lgkmcnt(0)
	v_mfma_f32_32x32x16_bf16 v[4:19], v[36:39], v[80:83], v[4:19]
	ds_read_b128 v[36:39], v43 offset:128
	s_waitcnt vmcnt(6) lgkmcnt(0)
	v_mfma_f32_32x32x16_bf16 v[20:35], v[36:39], v[76:79], v[20:35]
	ds_read_b128 v[36:39], v43 offset:8320
	s_waitcnt lgkmcnt(0)
	v_mfma_f32_32x32x16_bf16 v[4:19], v[36:39], v[76:79], v[4:19]
	s_cbranch_scc1 .LBB0_586
; __device__ __forceinline__ void bias_mask_tile(f32x16& p0, f32x16& p1, int dq, const float* bt) {
;     const float NEG = -__builtin_inff();
; #pragma unroll
;     for (int r = 0; r < 16; ++r) {
;         const int c = (r & 3) + 8 * (r >> 2);
;         const int d0 = dq - c, d1 = dq - c - 32;
;         const unsigned i0 = (unsigned)d0 < 255u ? (unsigned)d0 : 255u, i1 = (unsigned)d1 < 255u ? (unsigned)d1 : 255u;
;         const float b0 = bt[i0], b1 = bt[i1];
;         p0[r] = d0 >= 0 ? p0[r] + b0 : NEG;
;         p1[r] = d1 >= 0 ? p1[r] + b1 : NEG;
;     }
; }
	v_add_u32_e32 v115, 27, v125
	v_lshl_add_u32 v36, v115, 2, s64
	v_add_u32_e32 v36, 0xffffff14, v36
	ds_read_b32 v156, v36 offset:236
	ds_read_b32 v157, v36 offset:232
	ds_read_b32 v158, v36 offset:228
	ds_read_b32 v159, v36 offset:224
	ds_read_b32 v160, v36 offset:204
	ds_read_b32 v161, v36 offset:200
	ds_read_b32 v162, v36 offset:196
	ds_read_b32 v163, v36 offset:192
	ds_read_b32 v164, v36 offset:172
	ds_read_b32 v165, v36 offset:168
	ds_read_b32 v166, v36 offset:164
	ds_read_b32 v167, v36 offset:160
	ds_read_b32 v168, v36 offset:140
	ds_read_b32 v169, v36 offset:136
	ds_read_b32 v170, v36 offset:132
	v_cmp_lt_i32_e32 vcc, -1, v115
	v_cmp_lt_i32_e64 s[16:17], 0, v115
	s_waitcnt lgkmcnt(14)
	v_add_f32_e32 v20, v20, v156
	ds_read_b32 v171, v36 offset:128
	s_waitcnt lgkmcnt(14)
	v_add_f32_e32 v21, v21, v157
	ds_read_b32 v172, v36 offset:108
	v_cndmask_b32_e32 v20, v240, v20, vcc
	v_cndmask_b32_e64 v21, v240, v21, s[16:17]
	v_cmp_lt_i32_e32 vcc, 1, v115
	v_cmp_lt_i32_e64 s[16:17], 2, v115
	s_waitcnt lgkmcnt(14)
	v_add_f32_e32 v22, v22, v158
	ds_read_b32 v173, v36 offset:104
	s_waitcnt lgkmcnt(14)
	v_add_f32_e32 v23, v23, v159
	ds_read_b32 v174, v36 offset:100
	v_cndmask_b32_e32 v22, v240, v22, vcc
	v_cndmask_b32_e64 v23, v240, v23, s[16:17]
	v_cmp_lt_i32_e32 vcc, 7, v115
	v_cmp_lt_i32_e64 s[16:17], 8, v115
	s_waitcnt lgkmcnt(14)
	v_add_f32_e32 v24, v24, v160
	ds_read_b32 v175, v36 offset:96
	s_waitcnt lgkmcnt(14)
	v_add_f32_e32 v25, v25, v161
	ds_read_b32 v176, v36 offset:76
	v_cndmask_b32_e32 v24, v240, v24, vcc
	v_cndmask_b32_e64 v25, v240, v25, s[16:17]
	v_cmp_lt_i32_e32 vcc, 9, v115
	v_cmp_lt_i32_e64 s[16:17], 10, v115
	s_waitcnt lgkmcnt(14)
	v_add_f32_e32 v26, v26, v162
	ds_read_b32 v177, v36 offset:72
	s_waitcnt lgkmcnt(14)
	v_add_f32_e32 v27, v27, v163
	ds_read_b32 v178, v36 offset:68
	v_cndmask_b32_e32 v26, v240, v26, vcc
	v_cndmask_b32_e64 v27, v240, v27, s[16:17]
	v_cmp_lt_i32_e32 vcc, 15, v115
	v_cmp_lt_i32_e64 s[16:17], 16, v115
	s_waitcnt lgkmcnt(14)
	v_add_f32_e32 v28, v28, v164
	ds_read_b32 v179, v36 offset:64
	s_waitcnt lgkmcnt(14)
	v_add_f32_e32 v29, v29, v165
	ds_read_b32 v180, v36 offset:44
	v_cndmask_b32_e32 v28, v240, v28, vcc
	v_cndmask_b32_e64 v29, v240, v29, s[16:17]
	v_cmp_lt_i32_e32 vcc, 17, v115
	v_cmp_lt_i32_e64 s[16:17], 18, v115
	s_waitcnt lgkmcnt(14)
	v_add_f32_e32 v30, v30, v166
	ds_read_b32 v181, v36 offset:40
	s_waitcnt lgkmcnt(14)
	v_add_f32_e32 v31, v31, v167
	ds_read_b32 v182, v36 offset:36
	v_cndmask_b32_e32 v30, v240, v30, vcc
	v_cndmask_b32_e64 v31, v240, v31, s[16:17]
	v_cmp_lt_i32_e32 vcc, 23, v115
	v_cmp_lt_i32_e64 s[16:17], 24, v115
	s_waitcnt lgkmcnt(14)
	v_add_f32_e32 v32, v32, v168
	ds_read_b32 v183, v36 offset:32
	s_waitcnt lgkmcnt(14)
	v_add_f32_e32 v33, v33, v169
	ds_read_b32 v184, v36 offset:12
	v_cndmask_b32_e32 v32, v240, v32, vcc
	v_cndmask_b32_e64 v33, v240, v33, s[16:17]
	v_cmp_lt_i32_e32 vcc, 25, v115
	v_cmp_lt_i32_e64 s[16:17], 26, v115
	s_waitcnt lgkmcnt(14)
	v_add_f32_e32 v34, v34, v170
	ds_read_b32 v185, v36 offset:8
	s_waitcnt lgkmcnt(14)
	v_add_f32_e32 v35, v35, v171
	ds_read_b32 v186, v36 offset:4
	v_cndmask_b32_e32 v34, v240, v34, vcc
	v_cndmask_b32_e64 v35, v240, v35, s[16:17]
	v_cmp_lt_i32_e32 vcc, 31, v115
	v_cmp_lt_i32_e64 s[16:17], 32, v115
	s_waitcnt lgkmcnt(14)
	v_add_f32_e32 v4, v4, v172
	ds_read_b32 v187, v36 offset:0
	s_waitcnt lgkmcnt(14)
	v_add_f32_e32 v5, v5, v173
	v_cndmask_b32_e32 v4, v240, v4, vcc
	v_cndmask_b32_e64 v5, v240, v5, s[16:17]
	v_cmp_lt_i32_e32 vcc, 33, v115
	v_cmp_lt_i32_e64 s[16:17], 34, v115
	s_waitcnt lgkmcnt(13)
	v_add_f32_e32 v6, v6, v174
	s_waitcnt lgkmcnt(12)
	v_add_f32_e32 v7, v7, v175
	v_cndmask_b32_e32 v6, v240, v6, vcc
	v_cndmask_b32_e64 v7, v240, v7, s[16:17]
	v_cmp_lt_i32_e32 vcc, 39, v115
	v_cmp_lt_i32_e64 s[16:17], 40, v115
	s_waitcnt lgkmcnt(11)
	v_add_f32_e32 v8, v8, v176
	s_waitcnt lgkmcnt(10)
	v_add_f32_e32 v9, v9, v177
	v_cndmask_b32_e32 v8, v240, v8, vcc
	v_cndmask_b32_e64 v9, v240, v9, s[16:17]
	v_cmp_lt_i32_e32 vcc, 41, v115
	v_cmp_lt_i32_e64 s[16:17], 42, v115
	s_waitcnt lgkmcnt(9)
	v_add_f32_e32 v10, v10, v178
	s_waitcnt lgkmcnt(8)
	v_add_f32_e32 v11, v11, v179
	v_cndmask_b32_e32 v10, v240, v10, vcc
	v_cndmask_b32_e64 v11, v240, v11, s[16:17]
	v_cmp_lt_i32_e32 vcc, 47, v115
	v_cmp_lt_i32_e64 s[16:17], 48, v115
	s_waitcnt lgkmcnt(7)
	v_add_f32_e32 v12, v12, v180
	s_waitcnt lgkmcnt(6)
	v_add_f32_e32 v13, v13, v181
	v_cndmask_b32_e32 v12, v240, v12, vcc
	v_cndmask_b32_e64 v13, v240, v13, s[16:17]
	v_cmp_lt_i32_e32 vcc, 49, v115
	v_cmp_lt_i32_e64 s[16:17], 50, v115
	s_waitcnt lgkmcnt(5)
	v_add_f32_e32 v14, v14, v182
	s_waitcnt lgkmcnt(4)
	v_add_f32_e32 v15, v15, v183
	v_cndmask_b32_e32 v14, v240, v14, vcc
	v_cndmask_b32_e64 v15, v240, v15, s[16:17]
	v_cmp_lt_i32_e32 vcc, 55, v115
	v_cmp_lt_i32_e64 s[16:17], 56, v115
	s_waitcnt lgkmcnt(3)
	v_add_f32_e32 v16, v16, v184
	s_waitcnt lgkmcnt(2)
	v_add_f32_e32 v17, v17, v185
	v_cndmask_b32_e32 v16, v240, v16, vcc
	v_cndmask_b32_e64 v17, v240, v17, s[16:17]
	v_cmp_lt_i32_e32 vcc, 57, v115
	v_cmp_lt_i32_e64 s[16:17], 58, v115
	s_waitcnt lgkmcnt(1)
	v_add_f32_e32 v18, v18, v186
	s_waitcnt lgkmcnt(0)
	v_add_f32_e32 v19, v19, v187
	v_cndmask_b32_e32 v18, v240, v18, vcc
	v_cndmask_b32_e64 v19, v240, v19, s[16:17]

; __device__ __forceinline__ void qkt_rt(f32x16& p0, f32x16& p1, const char* Kb, int r32, int hi, const bf16x8* qr) {
;     p0 = f32x16{}; p1 = f32x16{};
;     const char* kb[4];
; #pragma unroll
;     for (int dd = 0; dd < 4; ++dd) kb[dd] = Kb + KSWZ(r32, (dd * 16 + hi * 8) * 2);
; #pragma unroll
;     for (int d0 = 0; d0 < 8; ++d0) { const char* a = kb[d0 & 3] + (d0 >> 2) * 128;
;         bf16x8 b0 = *reinterpret_cast<const bf16x8*>(a);
;         bf16x8 b1 = *reinterpret_cast<const bf16x8*>(a + 32 * 256);
;         p0 = __builtin_amdgcn_mfma_f32_32x32x16_bf16(b0, qr[d0], p0, 0, 0, 0);
;         p1 = __builtin_amdgcn_mfma_f32_32x32x16_bf16(b1, qr[d0], p1, 0, 0, 0); }
; }
.LBB0_592:
	s_add_i32 s10, s16, 0
	s_add_i32 s10, s10, 0x10000
	v_add3_u32 v44, s10, v121, v119
	ds_read_b128 v[4:7], v44
	ds_read_b128 v[8:11], v44 offset:8192
	v_add3_u32 v45, s10, v122, v119
	ds_read_b128 v[36:39], v45
	ds_read_b128 v[40:43], v45 offset:8192
	v_add3_u32 v46, s10, v123, v119
	s_waitcnt lgkmcnt(3)
	v_mfma_f32_32x32x16_bf16 v[20:35], v[4:7], v[104:107], 0
	v_add3_u32 v47, s10, v124, v119
	s_or_b32 s10, s84, 63
	s_cmp_le_i32 s10, s86
	s_waitcnt lgkmcnt(2)
	v_mfma_f32_32x32x16_bf16 v[4:19], v[8:11], v[104:107], 0
	s_waitcnt lgkmcnt(1)
	v_mfma_f32_32x32x16_bf16 v[20:35], v[36:39], v[100:103], v[20:35]
	s_waitcnt lgkmcnt(0)
	v_mfma_f32_32x32x16_bf16 v[4:19], v[40:43], v[100:103], v[4:19]
	ds_read_b128 v[36:39], v46
	ds_read_b128 v[40:43], v46 offset:8192
	s_waitcnt lgkmcnt(1)
	v_mfma_f32_32x32x16_bf16 v[20:35], v[36:39], v[96:99], v[20:35]
	s_waitcnt lgkmcnt(0)
	v_mfma_f32_32x32x16_bf16 v[4:19], v[40:43], v[96:99], v[4:19]
	ds_read_b128 v[36:39], v47
	ds_read_b128 v[40:43], v47 offset:8192
	s_waitcnt lgkmcnt(1)
	v_mfma_f32_32x32x16_bf16 v[20:35], v[36:39], v[92:95], v[20:35]
	s_waitcnt lgkmcnt(0)
	v_mfma_f32_32x32x16_bf16 v[4:19], v[40:43], v[92:95], v[4:19]
	ds_read_b128 v[36:39], v44 offset:128
	ds_read_b128 v[40:43], v44 offset:8320
	s_waitcnt lgkmcnt(1)
	v_mfma_f32_32x32x16_bf16 v[20:35], v[36:39], v[88:91], v[20:35]
	s_waitcnt lgkmcnt(0)
	v_mfma_f32_32x32x16_bf16 v[4:19], v[40:43], v[88:91], v[4:19]
	ds_read_b128 v[36:39], v45 offset:128
	ds_read_b128 v[40:43], v45 offset:8320
	s_waitcnt lgkmcnt(1)
	v_mfma_f32_32x32x16_bf16 v[20:35], v[36:39], v[84:87], v[20:35]
	s_waitcnt lgkmcnt(0)
	v_mfma_f32_32x32x16_bf16 v[4:19], v[40:43], v[84:87], v[4:19]
	ds_read_b128 v[36:39], v46 offset:128
	ds_read_b128 v[40:43], v46 offset:8320
	s_waitcnt lgkmcnt(1)
	v_mfma_f32_32x32x16_bf16 v[20:35], v[36:39], v[80:83], v[20:35]
	s_waitcnt lgkmcnt(0)
	v_mfma_f32_32x32x16_bf16 v[4:19], v[40:43], v[80:83], v[4:19]
	ds_read_b128 v[36:39], v47 offset:128
	ds_read_b128 v[40:43], v47 offset:8320
	s_waitcnt lgkmcnt(1)
	v_mfma_f32_32x32x16_bf16 v[20:35], v[36:39], v[76:79], v[20:35]
	s_waitcnt lgkmcnt(0)
	v_mfma_f32_32x32x16_bf16 v[4:19], v[40:43], v[76:79], v[4:19]
	s_cbranch_scc1 .LBB0_626
; __device__ __forceinline__ void bias_mask_tile(f32x16& p0, f32x16& p1, int dq, const float* bt) {
;     const float NEG = -__builtin_inff();
; #pragma unroll
;     for (int r = 0; r < 16; ++r) {
;         const int c = (r & 3) + 8 * (r >> 2);
;         const int d0 = dq - c, d1 = dq - c - 32;
;         const unsigned i0 = (unsigned)d0 < 255u ? (unsigned)d0 : 255u, i1 = (unsigned)d1 < 255u ? (unsigned)d1 : 255u;
;         const float b0 = bt[i0], b1 = bt[i1];
;         p0[r] = d0 >= 0 ? p0[r] + b0 : NEG;
;         p1[r] = d1 >= 0 ? p1[r] + b1 : NEG;
;     }
; }
	v_or_b32_e32 v36, s85, v211
	v_or_b32_e32 v37, s84, v114
	v_sub_u32_e32 v76, v36, v37
	v_lshl_add_u32 v36, v76, 2, s64
	v_add_u32_e32 v36, 0xffffff14, v36
	ds_read_b32 v156, v36 offset:236
	ds_read_b32 v157, v36 offset:232
	ds_read_b32 v158, v36 offset:228
	ds_read_b32 v159, v36 offset:224
	ds_read_b32 v160, v36 offset:204
	ds_read_b32 v161, v36 offset:200
	ds_read_b32 v162, v36 offset:196
	ds_read_b32 v163, v36 offset:192
	ds_read_b32 v164, v36 offset:172
	ds_read_b32 v165, v36 offset:168
	ds_read_b32 v166, v36 offset:164
	ds_read_b32 v167, v36 offset:160
	ds_read_b32 v168, v36 offset:140
	ds_read_b32 v169, v36 offset:136
	ds_read_b32 v170, v36 offset:132
	v_cmp_lt_i32_e32 vcc, -1, v76
	v_cmp_lt_i32_e64 s[16:17], 0, v76
	s_waitcnt lgkmcnt(14)
	v_add_f32_e32 v20, v20, v156
	ds_read_b32 v171, v36 offset:128
	s_waitcnt lgkmcnt(14)
	v_add_f32_e32 v21, v21, v157
	ds_read_b32 v172, v36 offset:108
	v_cndmask_b32_e32 v20, v240, v20, vcc
	v_cndmask_b32_e64 v21, v240, v21, s[16:17]
	v_cmp_lt_i32_e32 vcc, 1, v76
	v_cmp_lt_i32_e64 s[16:17], 2, v76
	s_waitcnt lgkmcnt(14)
	v_add_f32_e32 v22, v22, v158
	ds_read_b32 v173, v36 offset:104
	s_waitcnt lgkmcnt(14)
	v_add_f32_e32 v23, v23, v159
	ds_read_b32 v174, v36 offset:100
	v_cndmask_b32_e32 v22, v240, v22, vcc
	v_cndmask_b32_e64 v23, v240, v23, s[16:17]
	v_cmp_lt_i32_e32 vcc, 7, v76
	v_cmp_lt_i32_e64 s[16:17], 8, v76
	s_waitcnt lgkmcnt(14)
	v_add_f32_e32 v24, v24, v160
	ds_read_b32 v175, v36 offset:96
	s_waitcnt lgkmcnt(14)
	v_add_f32_e32 v25, v25, v161
	ds_read_b32 v176, v36 offset:76
	v_cndmask_b32_e32 v24, v240, v24, vcc
	v_cndmask_b32_e64 v25, v240, v25, s[16:17]
	v_cmp_lt_i32_e32 vcc, 9, v76
	v_cmp_lt_i32_e64 s[16:17], 10, v76
	s_waitcnt lgkmcnt(14)
	v_add_f32_e32 v26, v26, v162
	ds_read_b32 v177, v36 offset:72
	s_waitcnt lgkmcnt(14)
	v_add_f32_e32 v27, v27, v163
	ds_read_b32 v178, v36 offset:68
	v_cndmask_b32_e32 v26, v240, v26, vcc
	v_cndmask_b32_e64 v27, v240, v27, s[16:17]
	v_cmp_lt_i32_e32 vcc, 15, v76
	v_cmp_lt_i32_e64 s[16:17], 16, v76
	s_waitcnt lgkmcnt(14)
	v_add_f32_e32 v28, v28, v164
	ds_read_b32 v179, v36 offset:64
	s_waitcnt lgkmcnt(14)
	v_add_f32_e32 v29, v29, v165
	ds_read_b32 v180, v36 offset:44
	v_cndmask_b32_e32 v28, v240, v28, vcc
	v_cndmask_b32_e64 v29, v240, v29, s[16:17]
	v_cmp_lt_i32_e32 vcc, 17, v76
	v_cmp_lt_i32_e64 s[16:17], 18, v76
	s_waitcnt lgkmcnt(14)
	v_add_f32_e32 v30, v30, v166
	ds_read_b32 v181, v36 offset:40
	s_waitcnt lgkmcnt(14)
	v_add_f32_e32 v31, v31, v167
	ds_read_b32 v182, v36 offset:36
	v_cndmask_b32_e32 v30, v240, v30, vcc
	v_cndmask_b32_e64 v31, v240, v31, s[16:17]
	v_cmp_lt_i32_e32 vcc, 23, v76
	v_cmp_lt_i32_e64 s[16:17], 24, v76
	s_waitcnt lgkmcnt(14)
	v_add_f32_e32 v32, v32, v168
	ds_read_b32 v183, v36 offset:32
	s_waitcnt lgkmcnt(14)
	v_add_f32_e32 v33, v33, v169
	ds_read_b32 v184, v36 offset:12
	v_cndmask_b32_e32 v32, v240, v32, vcc
	v_cndmask_b32_e64 v33, v240, v33, s[16:17]
	v_cmp_lt_i32_e32 vcc, 25, v76
	v_cmp_lt_i32_e64 s[16:17], 26, v76
	s_waitcnt lgkmcnt(14)
	v_add_f32_e32 v34, v34, v170
	ds_read_b32 v185, v36 offset:8
	s_waitcnt lgkmcnt(14)
	v_add_f32_e32 v35, v35, v171
	ds_read_b32 v186, v36 offset:4
	v_cndmask_b32_e32 v34, v240, v34, vcc
	v_cndmask_b32_e64 v35, v240, v35, s[16:17]
	v_cmp_lt_i32_e32 vcc, 31, v76
	v_cmp_lt_i32_e64 s[16:17], 32, v76
	s_waitcnt lgkmcnt(14)
	v_add_f32_e32 v4, v4, v172
	ds_read_b32 v187, v36 offset:0
	s_waitcnt lgkmcnt(14)
	v_add_f32_e32 v5, v5, v173
	v_cndmask_b32_e32 v4, v240, v4, vcc
	v_cndmask_b32_e64 v5, v240, v5, s[16:17]
	v_cmp_lt_i32_e32 vcc, 33, v76
	v_cmp_lt_i32_e64 s[16:17], 34, v76
	s_waitcnt lgkmcnt(13)
	v_add_f32_e32 v6, v6, v174
	s_waitcnt lgkmcnt(12)
	v_add_f32_e32 v7, v7, v175
	v_cndmask_b32_e32 v6, v240, v6, vcc
	v_cndmask_b32_e64 v7, v240, v7, s[16:17]
	v_cmp_lt_i32_e32 vcc, 39, v76
	v_cmp_lt_i32_e64 s[16:17], 40, v76
	s_waitcnt lgkmcnt(11)
	v_add_f32_e32 v8, v8, v176
	s_waitcnt lgkmcnt(10)
	v_add_f32_e32 v9, v9, v177
	v_cndmask_b32_e32 v8, v240, v8, vcc
	v_cndmask_b32_e64 v9, v240, v9, s[16:17]
	v_cmp_lt_i32_e32 vcc, 41, v76
	v_cmp_lt_i32_e64 s[16:17], 42, v76
	s_waitcnt lgkmcnt(9)
	v_add_f32_e32 v10, v10, v178
	s_waitcnt lgkmcnt(8)
	v_add_f32_e32 v11, v11, v179
	v_cndmask_b32_e32 v10, v240, v10, vcc
	v_cndmask_b32_e64 v11, v240, v11, s[16:17]
	v_cmp_lt_i32_e32 vcc, 47, v76
	v_cmp_lt_i32_e64 s[16:17], 48, v76
	s_waitcnt lgkmcnt(7)
	v_add_f32_e32 v12, v12, v180
	s_waitcnt lgkmcnt(6)
	v_add_f32_e32 v13, v13, v181
	v_cndmask_b32_e32 v12, v240, v12, vcc
	v_cndmask_b32_e64 v13, v240, v13, s[16:17]
	v_cmp_lt_i32_e32 vcc, 49, v76
	v_cmp_lt_i32_e64 s[16:17], 50, v76
	s_waitcnt lgkmcnt(5)
	v_add_f32_e32 v14, v14, v182
	s_waitcnt lgkmcnt(4)
	v_add_f32_e32 v15, v15, v183
	v_cndmask_b32_e32 v14, v240, v14, vcc
	v_cndmask_b32_e64 v15, v240, v15, s[16:17]
	v_cmp_lt_i32_e32 vcc, 55, v76
	v_cmp_lt_i32_e64 s[16:17], 56, v76
	s_waitcnt lgkmcnt(3)
	v_add_f32_e32 v16, v16, v184
	s_waitcnt lgkmcnt(2)
	v_add_f32_e32 v17, v17, v185
	v_cndmask_b32_e32 v16, v240, v16, vcc
	v_cndmask_b32_e64 v17, v240, v17, s[16:17]
	v_cmp_lt_i32_e32 vcc, 57, v76
	v_cmp_lt_i32_e64 s[16:17], 58, v76
	s_waitcnt lgkmcnt(1)
	v_add_f32_e32 v18, v18, v186
	s_waitcnt lgkmcnt(0)
	v_add_f32_e32 v19, v19, v187
	v_cndmask_b32_e32 v18, v240, v18, vcc
	v_cndmask_b32_e64 v19, v240, v19, s[16:17]
